# grid-barrier seams: L1 invalidate issued at arrival (overlaps the barrier wait) instead of after the release
# speedup vs baseline: 1.0266x; 1.0092x over previous
; __device__ __forceinline__ unsigned xb_ld(unsigned* p)              { return __hip_atomic_load(p, __ATOMIC_RELAXED, __HIP_MEMORY_SCOPE_AGENT); }
; __device__ __forceinline__ unsigned xb_add(unsigned* p, unsigned v) { return __hip_atomic_fetch_add(p, v, __ATOMIC_RELAXED, __HIP_MEMORY_SCOPE_AGENT); }
; #define XB_SPIN(cond, bar) do { unsigned _sp = 0; while (cond) { __builtin_amdgcn_s_sleep(1); \
;     if ((++_sp & 255u) == 0u) { if (xb_ld(&(bar)[XB_TMO])) break; if (_sp > XB_SPIN_CAP) { atomicAdd(&(bar)[XB_TMO], 1u); break; } } } } while (0)
; __device__ __forceinline__ void xcd_barrier(const XcdBarrier& b) {
;     asm volatile("s_waitcnt vmcnt(0)" ::: "memory");
;     __syncthreads();
;     if (threadIdx.x == 0) {
;         unsigned* bar = b.bar;
;         __builtin_amdgcn_s_waitcnt(0);
;         unsigned nloc = b.st[0], nx = b.st[1];
;         if (nloc == 0u) { xcd_barrier_complete(bar, b.x, nloc, nx); b.st[0] = nloc; b.st[1] = nx; }
;         const unsigned old = xb_add(&bar[XB_XSUB(b.x)], 1u);
;         const unsigned gen = old / nloc;
;         if (old + 1u == (gen + 1u) * nloc) {
;             __builtin_amdgcn_fence(__ATOMIC_RELEASE, "agent");
;             asm volatile("s_waitcnt vmcnt(0)" ::: "memory");
;             const unsigned og = xb_add(&bar[XB_TOP], 1u);
;             const unsigned tg = og / nx;
;             if (og + 1u == (tg + 1u) * nx) xb_add(&bar[XB_TOPGEN], 1u);
;             else XB_SPIN(xb_ld(&bar[XB_TOPGEN]) == tg, bar);
;             __builtin_amdgcn_fence(__ATOMIC_ACQUIRE, "agent");
;             xb_add(&bar[XB_XGEN(b.x)], 1u);
;             asm volatile("s_waitcnt vmcnt(0)" ::: "memory");
;         } else {
;             XB_SPIN(xb_ld(&bar[XB_XGEN(b.x)]) == gen, bar);
;             __builtin_amdgcn_fence(__ATOMIC_ACQUIRE, "agent");
;             asm volatile("s_waitcnt vmcnt(0)" ::: "memory");
;         }
.LBB0_153:
	s_or_b64 exec, exec, s[10:11]
	v_cvt_f32_u32_e32 v4, v2
	s_waitcnt vmcnt(0)
	v_readfirstlane_b32 s8, v3
	buffer_inv sc1
	s_add_u32 s4, s4, 0x2400
	s_addc_u32 s5, s5, 0
	v_rcp_iflag_f32_e32 v4, v4
	v_add_u32_e32 v5, s8, v1
	v_mul_f32_e32 v3, 0x4f7ffffe, v4
	v_cvt_u32_f32_e32 v3, v3
	v_sub_u32_e32 v4, 0, v2
	v_mul_lo_u32 v1, v4, v3
	v_mul_hi_u32 v1, v3, v1
	v_add_u32_e32 v1, v3, v1
	v_mul_hi_u32 v1, v5, v1
	v_mul_lo_u32 v3, v1, v2
	v_sub_u32_e32 v3, v5, v3
	v_add_u32_e32 v4, 1, v1
	v_cmp_ge_u32_e32 vcc, v3, v2
	s_nop 1
	v_cndmask_b32_e32 v1, v1, v4, vcc
	v_sub_u32_e32 v4, v3, v2
	v_cndmask_b32_e32 v3, v3, v4, vcc
	v_add_u32_e32 v4, 1, v1
	v_cmp_ge_u32_e32 vcc, v3, v2
	v_add_u32_e32 v3, 1, v5
	s_nop 0
	v_cndmask_b32_e32 v1, v1, v4, vcc
	v_mul_lo_u32 v4, v2, v1
	v_add_u32_e32 v2, v4, v2
	v_cmp_ne_u32_e32 vcc, v3, v2
	s_and_saveexec_b64 s[8:9], vcc
	s_xor_b64 s[8:9], exec, s[8:9]
	s_cbranch_execz .LBB0_167
	s_waitcnt lgkmcnt(0)
	v_mov_b32_e32 v0, 0
	global_load_dword v2, v0, s[4:5] sc1
	s_waitcnt vmcnt(0)
	v_cmp_eq_u32_e32 vcc, v2, v1
	s_and_saveexec_b64 s[10:11], vcc
	s_cbranch_execz .LBB0_166
	s_mov_b32 s30, 1
	s_mov_b64 s[12:13], 0
	s_branch .LBB0_157

; __device__ __forceinline__ unsigned xb_ld(unsigned* p)              { return __hip_atomic_load(p, __ATOMIC_RELAXED, __HIP_MEMORY_SCOPE_AGENT); }
; #define XB_SPIN(cond, bar) do { unsigned _sp = 0; while (cond) { __builtin_amdgcn_s_sleep(1); \
;     if ((++_sp & 255u) == 0u) { if (xb_ld(&(bar)[XB_TMO])) break; if (_sp > XB_SPIN_CAP) { atomicAdd(&(bar)[XB_TMO], 1u); break; } } } } while (0)
; __device__ __forceinline__ void xcd_barrier(const XcdBarrier& b) {
;     ...
;         } else {
;             XB_SPIN(xb_ld(&bar[XB_XGEN(b.x)]) == gen, bar);
;             __builtin_amdgcn_fence(__ATOMIC_ACQUIRE, "agent");
;             asm volatile("s_waitcnt vmcnt(0)" ::: "memory");
.LBB0_166:
	s_or_b64 exec, exec, s[10:11]
	s_waitcnt vmcnt(0)
	s_waitcnt vmcnt(0)

; __device__ __forceinline__ unsigned xb_ld(unsigned* p)              { return __hip_atomic_load(p, __ATOMIC_RELAXED, __HIP_MEMORY_SCOPE_AGENT); }
; __device__ __forceinline__ unsigned xb_add(unsigned* p, unsigned v) { return __hip_atomic_fetch_add(p, v, __ATOMIC_RELAXED, __HIP_MEMORY_SCOPE_AGENT); }
; #define XB_SPIN(cond, bar) do { unsigned _sp = 0; while (cond) { __builtin_amdgcn_s_sleep(1); \
;     if ((++_sp & 255u) == 0u) { if (xb_ld(&(bar)[XB_TMO])) break; if (_sp > XB_SPIN_CAP) { atomicAdd(&(bar)[XB_TMO], 1u); break; } } } } while (0)
; __device__ __forceinline__ void xcd_barrier(const XcdBarrier& b) {
;     ...
;             __builtin_amdgcn_fence(__ATOMIC_RELEASE, "agent");
;             asm volatile("s_waitcnt vmcnt(0)" ::: "memory");
;             const unsigned og = xb_add(&bar[XB_TOP], 1u);
;             const unsigned tg = og / nx;
;             if (og + 1u == (tg + 1u) * nx) xb_add(&bar[XB_TOPGEN], 1u);
;             else XB_SPIN(xb_ld(&bar[XB_TOPGEN]) == tg, bar);
;             __builtin_amdgcn_fence(__ATOMIC_ACQUIRE, "agent");
;             xb_add(&bar[XB_XGEN(b.x)], 1u);
.LBB0_184:
	s_or_b64 exec, exec, s[2:3]
	s_mov_b64 s[2:3], exec
	v_mbcnt_lo_u32_b32 v0, s2, 0
	v_mbcnt_hi_u32_b32 v0, s3, v0
	v_cmp_eq_u32_e32 vcc, 0, v0
	s_waitcnt vmcnt(0)
	s_and_saveexec_b64 s[8:9], vcc
	s_cbranch_execz .LBB0_186
	s_bcnt1_i32_b64 s2, s[2:3]
	v_mov_b32_e32 v0, 0
	v_mov_b32_e32 v1, s2
	global_atomic_add v0, v1, s[4:5]

; __device__ __forceinline__ unsigned xb_ld(unsigned* p)              { return __hip_atomic_load(p, __ATOMIC_RELAXED, __HIP_MEMORY_SCOPE_AGENT); }
; __device__ __forceinline__ unsigned xb_add(unsigned* p, unsigned v) { return __hip_atomic_fetch_add(p, v, __ATOMIC_RELAXED, __HIP_MEMORY_SCOPE_AGENT); }
; #define XB_SPIN(cond, bar) do { unsigned _sp = 0; while (cond) { __builtin_amdgcn_s_sleep(1); \
;     if ((++_sp & 255u) == 0u) { if (xb_ld(&(bar)[XB_TMO])) break; if (_sp > XB_SPIN_CAP) { atomicAdd(&(bar)[XB_TMO], 1u); break; } } } } while (0)
; __device__ __forceinline__ void xcd_barrier(const XcdBarrier& b) {
;     asm volatile("s_waitcnt vmcnt(0)" ::: "memory");
;     __syncthreads();
;     if (threadIdx.x == 0) {
;         unsigned* bar = b.bar;
;         __builtin_amdgcn_s_waitcnt(0);
;         unsigned nloc = b.st[0], nx = b.st[1];
;         if (nloc == 0u) { xcd_barrier_complete(bar, b.x, nloc, nx); b.st[0] = nloc; b.st[1] = nx; }
;         const unsigned old = xb_add(&bar[XB_XSUB(b.x)], 1u);
;         const unsigned gen = old / nloc;
;         if (old + 1u == (gen + 1u) * nloc) {
;             __builtin_amdgcn_fence(__ATOMIC_RELEASE, "agent");
;             asm volatile("s_waitcnt vmcnt(0)" ::: "memory");
;             const unsigned og = xb_add(&bar[XB_TOP], 1u);
;             const unsigned tg = og / nx;
;             if (og + 1u == (tg + 1u) * nx) xb_add(&bar[XB_TOPGEN], 1u);
;             else XB_SPIN(xb_ld(&bar[XB_TOPGEN]) == tg, bar);
;             __builtin_amdgcn_fence(__ATOMIC_ACQUIRE, "agent");
;             xb_add(&bar[XB_XGEN(b.x)], 1u);
;             asm volatile("s_waitcnt vmcnt(0)" ::: "memory");
;         } else {
;             XB_SPIN(xb_ld(&bar[XB_XGEN(b.x)]) == gen, bar);
;             __builtin_amdgcn_fence(__ATOMIC_ACQUIRE, "agent");
;             asm volatile("s_waitcnt vmcnt(0)" ::: "memory");
;         }
.LBB0_255:
	s_or_b64 exec, exec, s[10:11]
	v_cvt_f32_u32_e32 v4, v2
	s_waitcnt vmcnt(0)
	v_readfirstlane_b32 s8, v3
	buffer_inv sc1
	s_add_u32 s4, s4, 0x2400
	s_addc_u32 s5, s5, 0
	v_rcp_iflag_f32_e32 v4, v4
	v_add_u32_e32 v5, s8, v1
	v_mul_f32_e32 v3, 0x4f7ffffe, v4
	v_cvt_u32_f32_e32 v3, v3
	v_sub_u32_e32 v4, 0, v2
	v_mul_lo_u32 v1, v4, v3
	v_mul_hi_u32 v1, v3, v1
	v_add_u32_e32 v1, v3, v1
	v_mul_hi_u32 v1, v5, v1
	v_mul_lo_u32 v3, v1, v2
	v_sub_u32_e32 v3, v5, v3
	v_add_u32_e32 v4, 1, v1
	v_cmp_ge_u32_e32 vcc, v3, v2
	s_nop 1
	v_cndmask_b32_e32 v1, v1, v4, vcc
	v_sub_u32_e32 v4, v3, v2
	v_cndmask_b32_e32 v3, v3, v4, vcc
	v_add_u32_e32 v4, 1, v1
	v_cmp_ge_u32_e32 vcc, v3, v2
	v_add_u32_e32 v3, 1, v5
	s_nop 0
	v_cndmask_b32_e32 v1, v1, v4, vcc
	v_mul_lo_u32 v4, v2, v1
	v_add_u32_e32 v2, v4, v2
	v_cmp_ne_u32_e32 vcc, v3, v2
	s_and_saveexec_b64 s[8:9], vcc
	s_xor_b64 s[8:9], exec, s[8:9]
	s_cbranch_execz .LBB0_269
	s_waitcnt lgkmcnt(0)
	v_mov_b32_e32 v0, 0
	global_load_dword v2, v0, s[4:5] sc1
	s_waitcnt vmcnt(0)
	v_cmp_eq_u32_e32 vcc, v2, v1
	s_and_saveexec_b64 s[10:11], vcc
	s_cbranch_execz .LBB0_268
	s_mov_b32 s24, 1
	s_mov_b64 s[12:13], 0
	s_branch .LBB0_259

; __device__ __forceinline__ unsigned xb_ld(unsigned* p)              { return __hip_atomic_load(p, __ATOMIC_RELAXED, __HIP_MEMORY_SCOPE_AGENT); }
; __device__ __forceinline__ unsigned xb_add(unsigned* p, unsigned v) { return __hip_atomic_fetch_add(p, v, __ATOMIC_RELAXED, __HIP_MEMORY_SCOPE_AGENT); }
; #define XB_SPIN(cond, bar) do { unsigned _sp = 0; while (cond) { __builtin_amdgcn_s_sleep(1); \
;     if ((++_sp & 255u) == 0u) { if (xb_ld(&(bar)[XB_TMO])) break; if (_sp > XB_SPIN_CAP) { atomicAdd(&(bar)[XB_TMO], 1u); break; } } } } while (0)
; __device__ __forceinline__ void xcd_barrier(const XcdBarrier& b) {
;     asm volatile("s_waitcnt vmcnt(0)" ::: "memory");
;     __syncthreads();
;     if (threadIdx.x == 0) {
;         unsigned* bar = b.bar;
;         __builtin_amdgcn_s_waitcnt(0);
;         unsigned nloc = b.st[0], nx = b.st[1];
;         if (nloc == 0u) { xcd_barrier_complete(bar, b.x, nloc, nx); b.st[0] = nloc; b.st[1] = nx; }
;         const unsigned old = xb_add(&bar[XB_XSUB(b.x)], 1u);
;         const unsigned gen = old / nloc;
;         if (old + 1u == (gen + 1u) * nloc) {
;             __builtin_amdgcn_fence(__ATOMIC_RELEASE, "agent");
;             asm volatile("s_waitcnt vmcnt(0)" ::: "memory");
;             const unsigned og = xb_add(&bar[XB_TOP], 1u);
;             const unsigned tg = og / nx;
;             if (og + 1u == (tg + 1u) * nx) xb_add(&bar[XB_TOPGEN], 1u);
;             else XB_SPIN(xb_ld(&bar[XB_TOPGEN]) == tg, bar);
;             __builtin_amdgcn_fence(__ATOMIC_ACQUIRE, "agent");
;             xb_add(&bar[XB_XGEN(b.x)], 1u);
;             asm volatile("s_waitcnt vmcnt(0)" ::: "memory");
;         } else {
;             XB_SPIN(xb_ld(&bar[XB_XGEN(b.x)]) == gen, bar);
;             __builtin_amdgcn_fence(__ATOMIC_ACQUIRE, "agent");
;             asm volatile("s_waitcnt vmcnt(0)" ::: "memory");
;         }
.LBB0_365:
	s_or_b64 exec, exec, s[6:7]
	v_cvt_f32_u32_e32 v4, v2
	s_waitcnt vmcnt(0)
	v_readfirstlane_b32 s4, v3
	buffer_inv sc1
	v_sub_u32_e32 v3, 0, v2
	v_rcp_iflag_f32_e32 v4, v4
	v_add_u32_e32 v5, s4, v1
	v_mul_f32_e32 v4, 0x4f7ffffe, v4
	v_cvt_u32_f32_e32 v4, v4
	v_mul_lo_u32 v1, v3, v4
	v_mul_hi_u32 v1, v4, v1
	v_add_u32_e32 v1, v4, v1
	v_mul_hi_u32 v1, v5, v1
	v_mul_lo_u32 v3, v1, v2
	v_sub_u32_e32 v3, v5, v3
	v_add_u32_e32 v4, 1, v1
	v_cmp_ge_u32_e32 vcc, v3, v2
	s_nop 1
	v_cndmask_b32_e32 v1, v1, v4, vcc
	v_sub_u32_e32 v4, v3, v2
	v_cndmask_b32_e32 v3, v3, v4, vcc
	v_add_u32_e32 v4, 1, v1
	v_cmp_ge_u32_e32 vcc, v3, v2
	v_add_u32_e32 v3, 1, v5
	s_nop 0
	v_cndmask_b32_e32 v1, v1, v4, vcc
	v_mul_lo_u32 v4, v2, v1
	v_add_u32_e32 v2, v4, v2
	v_cmp_ne_u32_e32 vcc, v3, v2
	s_and_saveexec_b64 s[4:5], vcc
	s_xor_b64 s[4:5], exec, s[4:5]
	s_cbranch_execz .LBB0_379
	s_waitcnt lgkmcnt(0)
	v_mov_b32_e32 v0, 0x2000
	global_load_dword v0, v0, s[2:3] offset:1024 sc1
	s_add_u32 s10, s2, 0x2400
	s_addc_u32 s11, s3, 0
	s_waitcnt vmcnt(0)
	v_cmp_eq_u32_e32 vcc, v0, v1
	s_and_saveexec_b64 s[6:7], vcc
	s_cbranch_execz .LBB0_378
	s_add_u32 s8, s86, 0x2b62a00
	s_addc_u32 s9, s87, 0
	s_mov_b32 s24, 1
	s_mov_b64 s[12:13], 0
	v_mov_b32_e32 v0, 0
	s_branch .LBB0_369

; __device__ __forceinline__ unsigned xb_ld(unsigned* p)              { return __hip_atomic_load(p, __ATOMIC_RELAXED, __HIP_MEMORY_SCOPE_AGENT); }
; #define XB_SPIN(cond, bar) do { unsigned _sp = 0; while (cond) { __builtin_amdgcn_s_sleep(1); \
;     if ((++_sp & 255u) == 0u) { if (xb_ld(&(bar)[XB_TMO])) break; if (_sp > XB_SPIN_CAP) { atomicAdd(&(bar)[XB_TMO], 1u); break; } } } } while (0)
; __device__ __forceinline__ void xcd_barrier(const XcdBarrier& b) {
;     ...
;         } else {
;             XB_SPIN(xb_ld(&bar[XB_XGEN(b.x)]) == gen, bar);
;             __builtin_amdgcn_fence(__ATOMIC_ACQUIRE, "agent");
;             asm volatile("s_waitcnt vmcnt(0)" ::: "memory");
.LBB0_378:
	s_or_b64 exec, exec, s[6:7]
	s_waitcnt vmcnt(0)
	s_waitcnt vmcnt(0)

; __device__ __forceinline__ unsigned xb_ld(unsigned* p)              { return __hip_atomic_load(p, __ATOMIC_RELAXED, __HIP_MEMORY_SCOPE_AGENT); }
; __device__ __forceinline__ unsigned xb_add(unsigned* p, unsigned v) { return __hip_atomic_fetch_add(p, v, __ATOMIC_RELAXED, __HIP_MEMORY_SCOPE_AGENT); }
; #define XB_SPIN(cond, bar) do { unsigned _sp = 0; while (cond) { __builtin_amdgcn_s_sleep(1); \
;     if ((++_sp & 255u) == 0u) { if (xb_ld(&(bar)[XB_TMO])) break; if (_sp > XB_SPIN_CAP) { atomicAdd(&(bar)[XB_TMO], 1u); break; } } } } while (0)
; __device__ __forceinline__ void xcd_barrier(const XcdBarrier& b) {
;     ...
;             __builtin_amdgcn_fence(__ATOMIC_RELEASE, "agent");
;             asm volatile("s_waitcnt vmcnt(0)" ::: "memory");
;             const unsigned og = xb_add(&bar[XB_TOP], 1u);
;             const unsigned tg = og / nx;
;             if (og + 1u == (tg + 1u) * nx) xb_add(&bar[XB_TOPGEN], 1u);
;             else XB_SPIN(xb_ld(&bar[XB_TOPGEN]) == tg, bar);
;             __builtin_amdgcn_fence(__ATOMIC_ACQUIRE, "agent");
;             xb_add(&bar[XB_XGEN(b.x)], 1u);
.LBB0_396:
	s_or_b64 exec, exec, s[4:5]
	s_mov_b64 s[4:5], exec
	v_mbcnt_lo_u32_b32 v0, s4, 0
	v_mbcnt_hi_u32_b32 v0, s5, v0
	v_cmp_eq_u32_e32 vcc, 0, v0
	s_waitcnt vmcnt(0)
	s_and_saveexec_b64 s[6:7], vcc
	s_cbranch_execz .LBB0_398
	s_bcnt1_i32_b64 s4, s[4:5]
	v_mov_b32_e32 v0, 0x2000
	v_mov_b32_e32 v1, s4
	global_atomic_add v0, v1, s[2:3] offset:1024

; __device__ __forceinline__ unsigned xb_ld(unsigned* p)              { return __hip_atomic_load(p, __ATOMIC_RELAXED, __HIP_MEMORY_SCOPE_AGENT); }
; __device__ __forceinline__ unsigned xb_add(unsigned* p, unsigned v) { return __hip_atomic_fetch_add(p, v, __ATOMIC_RELAXED, __HIP_MEMORY_SCOPE_AGENT); }
; #define XB_SPIN(cond, bar) do { unsigned _sp = 0; while (cond) { __builtin_amdgcn_s_sleep(1); \
;     if ((++_sp & 255u) == 0u) { if (xb_ld(&(bar)[XB_TMO])) break; if (_sp > XB_SPIN_CAP) { atomicAdd(&(bar)[XB_TMO], 1u); break; } } } } while (0)
; __device__ __forceinline__ void xcd_barrier(const XcdBarrier& b) {
;     asm volatile("s_waitcnt vmcnt(0)" ::: "memory");
;     __syncthreads();
;     if (threadIdx.x == 0) {
;         unsigned* bar = b.bar;
;         __builtin_amdgcn_s_waitcnt(0);
;         unsigned nloc = b.st[0], nx = b.st[1];
;         if (nloc == 0u) { xcd_barrier_complete(bar, b.x, nloc, nx); b.st[0] = nloc; b.st[1] = nx; }
;         const unsigned old = xb_add(&bar[XB_XSUB(b.x)], 1u);
;         const unsigned gen = old / nloc;
;         if (old + 1u == (gen + 1u) * nloc) {
;             __builtin_amdgcn_fence(__ATOMIC_RELEASE, "agent");
;             asm volatile("s_waitcnt vmcnt(0)" ::: "memory");
;             const unsigned og = xb_add(&bar[XB_TOP], 1u);
;             const unsigned tg = og / nx;
;             if (og + 1u == (tg + 1u) * nx) xb_add(&bar[XB_TOPGEN], 1u);
;             else XB_SPIN(xb_ld(&bar[XB_TOPGEN]) == tg, bar);
;             __builtin_amdgcn_fence(__ATOMIC_ACQUIRE, "agent");
;             xb_add(&bar[XB_XGEN(b.x)], 1u);
;             asm volatile("s_waitcnt vmcnt(0)" ::: "memory");
;         } else {
;             XB_SPIN(xb_ld(&bar[XB_XGEN(b.x)]) == gen, bar);
;             __builtin_amdgcn_fence(__ATOMIC_ACQUIRE, "agent");
;             asm volatile("s_waitcnt vmcnt(0)" ::: "memory");
;         }
.LBB0_485:
	s_or_b64 exec, exec, s[8:9]
	v_cvt_f32_u32_e32 v4, v2
	s_waitcnt vmcnt(0)
	v_readfirstlane_b32 s6, v3
	buffer_inv sc1
	s_add_u32 s4, s4, 0x2400
	s_addc_u32 s5, s5, 0
	v_rcp_iflag_f32_e32 v4, v4
	v_add_u32_e32 v5, s6, v1
	v_mul_f32_e32 v3, 0x4f7ffffe, v4
	v_cvt_u32_f32_e32 v3, v3
	v_sub_u32_e32 v4, 0, v2
	v_mul_lo_u32 v1, v4, v3
	v_mul_hi_u32 v1, v3, v1
	v_add_u32_e32 v1, v3, v1
	v_mul_hi_u32 v1, v5, v1
	v_mul_lo_u32 v3, v1, v2
	v_sub_u32_e32 v3, v5, v3
	v_add_u32_e32 v4, 1, v1
	v_cmp_ge_u32_e32 vcc, v3, v2
	s_nop 1
	v_cndmask_b32_e32 v1, v1, v4, vcc
	v_sub_u32_e32 v4, v3, v2
	v_cndmask_b32_e32 v3, v3, v4, vcc
	v_add_u32_e32 v4, 1, v1
	v_cmp_ge_u32_e32 vcc, v3, v2
	v_add_u32_e32 v3, 1, v5
	s_nop 0
	v_cndmask_b32_e32 v1, v1, v4, vcc
	v_mul_lo_u32 v4, v2, v1
	v_add_u32_e32 v2, v4, v2
	v_cmp_ne_u32_e32 vcc, v3, v2
	s_and_saveexec_b64 s[6:7], vcc
	s_xor_b64 s[6:7], exec, s[6:7]
	s_cbranch_execz .LBB0_499
	s_waitcnt lgkmcnt(0)
	v_mov_b32_e32 v0, 0
	global_load_dword v2, v0, s[4:5] sc1
	s_waitcnt vmcnt(0)
	v_cmp_eq_u32_e32 vcc, v2, v1
	s_and_saveexec_b64 s[8:9], vcc
	s_cbranch_execz .LBB0_498
	s_mov_b32 s20, 1
	s_mov_b64 s[10:11], 0
	s_branch .LBB0_489

; __device__ __forceinline__ unsigned xb_ld(unsigned* p)              { return __hip_atomic_load(p, __ATOMIC_RELAXED, __HIP_MEMORY_SCOPE_AGENT); }
; #define XB_SPIN(cond, bar) do { unsigned _sp = 0; while (cond) { __builtin_amdgcn_s_sleep(1); \
;     if ((++_sp & 255u) == 0u) { if (xb_ld(&(bar)[XB_TMO])) break; if (_sp > XB_SPIN_CAP) { atomicAdd(&(bar)[XB_TMO], 1u); break; } } } } while (0)
; __device__ __forceinline__ void xcd_barrier(const XcdBarrier& b) {
;     ...
;         } else {
;             XB_SPIN(xb_ld(&bar[XB_XGEN(b.x)]) == gen, bar);
;             __builtin_amdgcn_fence(__ATOMIC_ACQUIRE, "agent");
;             asm volatile("s_waitcnt vmcnt(0)" ::: "memory");
.LBB0_498:
	s_or_b64 exec, exec, s[8:9]
	s_waitcnt vmcnt(0)
	s_waitcnt vmcnt(0)

; __device__ __forceinline__ unsigned xb_ld(unsigned* p)              { return __hip_atomic_load(p, __ATOMIC_RELAXED, __HIP_MEMORY_SCOPE_AGENT); }
; __device__ __forceinline__ unsigned xb_add(unsigned* p, unsigned v) { return __hip_atomic_fetch_add(p, v, __ATOMIC_RELAXED, __HIP_MEMORY_SCOPE_AGENT); }
; #define XB_SPIN(cond, bar) do { unsigned _sp = 0; while (cond) { __builtin_amdgcn_s_sleep(1); \
;     if ((++_sp & 255u) == 0u) { if (xb_ld(&(bar)[XB_TMO])) break; if (_sp > XB_SPIN_CAP) { atomicAdd(&(bar)[XB_TMO], 1u); break; } } } } while (0)
; __device__ __forceinline__ void xcd_barrier(const XcdBarrier& b) {
;     ...
;             __builtin_amdgcn_fence(__ATOMIC_RELEASE, "agent");
;             asm volatile("s_waitcnt vmcnt(0)" ::: "memory");
;             const unsigned og = xb_add(&bar[XB_TOP], 1u);
;             const unsigned tg = og / nx;
;             if (og + 1u == (tg + 1u) * nx) xb_add(&bar[XB_TOPGEN], 1u);
;             else XB_SPIN(xb_ld(&bar[XB_TOPGEN]) == tg, bar);
;             __builtin_amdgcn_fence(__ATOMIC_ACQUIRE, "agent");
;             xb_add(&bar[XB_XGEN(b.x)], 1u);
.LBB0_516:
	s_or_b64 exec, exec, s[2:3]
	s_mov_b64 s[2:3], exec
	v_mbcnt_lo_u32_b32 v0, s2, 0
	v_mbcnt_hi_u32_b32 v0, s3, v0
	v_cmp_eq_u32_e32 vcc, 0, v0
	s_waitcnt vmcnt(0)
	s_and_saveexec_b64 s[6:7], vcc
	s_cbranch_execz .LBB0_518
	s_bcnt1_i32_b64 s2, s[2:3]
	v_mov_b32_e32 v0, 0
	v_mov_b32_e32 v1, s2
	global_atomic_add v0, v1, s[4:5]

; __device__ __forceinline__ unsigned xb_ld(unsigned* p)              { return __hip_atomic_load(p, __ATOMIC_RELAXED, __HIP_MEMORY_SCOPE_AGENT); }
; __device__ __forceinline__ unsigned xb_add(unsigned* p, unsigned v) { return __hip_atomic_fetch_add(p, v, __ATOMIC_RELAXED, __HIP_MEMORY_SCOPE_AGENT); }
; #define XB_SPIN(cond, bar) do { unsigned _sp = 0; while (cond) { __builtin_amdgcn_s_sleep(1); \
;     if ((++_sp & 255u) == 0u) { if (xb_ld(&(bar)[XB_TMO])) break; if (_sp > XB_SPIN_CAP) { atomicAdd(&(bar)[XB_TMO], 1u); break; } } } } while (0)
; __device__ __forceinline__ void xcd_barrier(const XcdBarrier& b) {
;     asm volatile("s_waitcnt vmcnt(0)" ::: "memory");
;     __syncthreads();
;     if (threadIdx.x == 0) {
;         unsigned* bar = b.bar;
;         __builtin_amdgcn_s_waitcnt(0);
;         unsigned nloc = b.st[0], nx = b.st[1];
;         if (nloc == 0u) { xcd_barrier_complete(bar, b.x, nloc, nx); b.st[0] = nloc; b.st[1] = nx; }
;         const unsigned old = xb_add(&bar[XB_XSUB(b.x)], 1u);
;         const unsigned gen = old / nloc;
;         if (old + 1u == (gen + 1u) * nloc) {
;             __builtin_amdgcn_fence(__ATOMIC_RELEASE, "agent");
;             asm volatile("s_waitcnt vmcnt(0)" ::: "memory");
;             const unsigned og = xb_add(&bar[XB_TOP], 1u);
;             const unsigned tg = og / nx;
;             if (og + 1u == (tg + 1u) * nx) xb_add(&bar[XB_TOPGEN], 1u);
;             else XB_SPIN(xb_ld(&bar[XB_TOPGEN]) == tg, bar);
;             __builtin_amdgcn_fence(__ATOMIC_ACQUIRE, "agent");
;             xb_add(&bar[XB_XGEN(b.x)], 1u);
;             asm volatile("s_waitcnt vmcnt(0)" ::: "memory");
;         } else {
;             XB_SPIN(xb_ld(&bar[XB_XGEN(b.x)]) == gen, bar);
;             __builtin_amdgcn_fence(__ATOMIC_ACQUIRE, "agent");
;             asm volatile("s_waitcnt vmcnt(0)" ::: "memory");
;         }
.LBB0_578:
	s_or_b64 exec, exec, s[6:7]
	v_cvt_f32_u32_e32 v4, v2
	s_waitcnt vmcnt(0)
	v_readfirstlane_b32 s4, v3
	buffer_inv sc1
	v_sub_u32_e32 v3, 0, v2
	v_rcp_iflag_f32_e32 v4, v4
	v_add_u32_e32 v5, s4, v1
	v_mul_f32_e32 v4, 0x4f7ffffe, v4
	v_cvt_u32_f32_e32 v4, v4
	v_mul_lo_u32 v1, v3, v4
	v_mul_hi_u32 v1, v4, v1
	v_add_u32_e32 v1, v4, v1
	v_mul_hi_u32 v1, v5, v1
	v_mul_lo_u32 v3, v1, v2
	v_sub_u32_e32 v3, v5, v3
	v_add_u32_e32 v4, 1, v1
	v_cmp_ge_u32_e32 vcc, v3, v2
	s_nop 1
	v_cndmask_b32_e32 v1, v1, v4, vcc
	v_sub_u32_e32 v4, v3, v2
	v_cndmask_b32_e32 v3, v3, v4, vcc
	v_add_u32_e32 v4, 1, v1
	v_cmp_ge_u32_e32 vcc, v3, v2
	v_add_u32_e32 v3, 1, v5
	s_nop 0
	v_cndmask_b32_e32 v1, v1, v4, vcc
	v_mul_lo_u32 v4, v2, v1
	v_add_u32_e32 v2, v4, v2
	v_cmp_ne_u32_e32 vcc, v3, v2
	s_and_saveexec_b64 s[4:5], vcc
	s_xor_b64 s[4:5], exec, s[4:5]
	s_cbranch_execz .LBB0_592
	s_waitcnt lgkmcnt(0)
	v_mov_b32_e32 v0, 0x2000
	global_load_dword v0, v0, s[2:3] offset:1024 sc1
	s_add_u32 s10, s2, 0x2400
	s_addc_u32 s11, s3, 0
	s_waitcnt vmcnt(0)
	v_cmp_eq_u32_e32 vcc, v0, v1
	s_and_saveexec_b64 s[6:7], vcc
	s_cbranch_execz .LBB0_591
	s_add_u32 s8, s86, 0x2b62a00
	s_addc_u32 s9, s87, 0
	s_mov_b32 s22, 1
	s_mov_b64 s[12:13], 0
	v_mov_b32_e32 v0, 0
	s_branch .LBB0_582

; __device__ __forceinline__ unsigned xb_ld(unsigned* p)              { return __hip_atomic_load(p, __ATOMIC_RELAXED, __HIP_MEMORY_SCOPE_AGENT); }
; __device__ __forceinline__ unsigned xb_add(unsigned* p, unsigned v) { return __hip_atomic_fetch_add(p, v, __ATOMIC_RELAXED, __HIP_MEMORY_SCOPE_AGENT); }
; #define XB_SPIN(cond, bar) do { unsigned _sp = 0; while (cond) { __builtin_amdgcn_s_sleep(1); \
;     if ((++_sp & 255u) == 0u) { if (xb_ld(&(bar)[XB_TMO])) break; if (_sp > XB_SPIN_CAP) { atomicAdd(&(bar)[XB_TMO], 1u); break; } } } } while (0)
; __device__ __forceinline__ void xcd_barrier(const XcdBarrier& b) {
;     asm volatile("s_waitcnt vmcnt(0)" ::: "memory");
;     __syncthreads();
;     if (threadIdx.x == 0) {
;         unsigned* bar = b.bar;
;         __builtin_amdgcn_s_waitcnt(0);
;         unsigned nloc = b.st[0], nx = b.st[1];
;         if (nloc == 0u) { xcd_barrier_complete(bar, b.x, nloc, nx); b.st[0] = nloc; b.st[1] = nx; }
;         const unsigned old = xb_add(&bar[XB_XSUB(b.x)], 1u);
;         const unsigned gen = old / nloc;
;         if (old + 1u == (gen + 1u) * nloc) {
;             __builtin_amdgcn_fence(__ATOMIC_RELEASE, "agent");
;             asm volatile("s_waitcnt vmcnt(0)" ::: "memory");
;             const unsigned og = xb_add(&bar[XB_TOP], 1u);
;             const unsigned tg = og / nx;
;             if (og + 1u == (tg + 1u) * nx) xb_add(&bar[XB_TOPGEN], 1u);
;             else XB_SPIN(xb_ld(&bar[XB_TOPGEN]) == tg, bar);
;             __builtin_amdgcn_fence(__ATOMIC_ACQUIRE, "agent");
;             xb_add(&bar[XB_XGEN(b.x)], 1u);
;             asm volatile("s_waitcnt vmcnt(0)" ::: "memory");
;         } else {
;             XB_SPIN(xb_ld(&bar[XB_XGEN(b.x)]) == gen, bar);
;             __builtin_amdgcn_fence(__ATOMIC_ACQUIRE, "agent");
;             asm volatile("s_waitcnt vmcnt(0)" ::: "memory");
;         }
.LBB0_1058:
	s_or_b64 exec, exec, s[8:9]
	v_cvt_f32_u32_e32 v4, v2
	s_waitcnt vmcnt(0)
	v_readfirstlane_b32 s6, v3
	buffer_inv sc1
	v_sub_u32_e32 v3, 0, v2
	v_rcp_iflag_f32_e32 v4, v4
	v_add_u32_e32 v5, s6, v1
	v_mul_f32_e32 v4, 0x4f7ffffe, v4
	v_cvt_u32_f32_e32 v4, v4
	v_mul_lo_u32 v1, v3, v4
	v_mul_hi_u32 v1, v4, v1
	v_add_u32_e32 v1, v4, v1
	v_mul_hi_u32 v1, v5, v1
	v_mul_lo_u32 v3, v1, v2
	v_sub_u32_e32 v3, v5, v3
	v_add_u32_e32 v4, 1, v1
	v_cmp_ge_u32_e32 vcc, v3, v2
	s_nop 1
	v_cndmask_b32_e32 v1, v1, v4, vcc
	v_sub_u32_e32 v4, v3, v2
	v_cndmask_b32_e32 v3, v3, v4, vcc
	v_add_u32_e32 v4, 1, v1
	v_cmp_ge_u32_e32 vcc, v3, v2
	v_add_u32_e32 v3, 1, v5
	s_nop 0
	v_cndmask_b32_e32 v1, v1, v4, vcc
	v_mul_lo_u32 v4, v2, v1
	v_add_u32_e32 v2, v4, v2
	v_cmp_ne_u32_e32 vcc, v3, v2
	s_and_saveexec_b64 s[6:7], vcc
	s_xor_b64 s[6:7], exec, s[6:7]
	s_cbranch_execz .LBB0_1072
	s_waitcnt lgkmcnt(0)
	v_mov_b32_e32 v0, 0x2000
	global_load_dword v0, v0, s[4:5] offset:1024 sc1
	s_add_u32 s12, s4, 0x2400
	s_addc_u32 s13, s5, 0
	s_waitcnt vmcnt(0)
	v_cmp_eq_u32_e32 vcc, v0, v1
	s_and_saveexec_b64 s[8:9], vcc
	s_cbranch_execz .LBB0_1071
	s_add_u32 s10, s86, 0x2b62a00
	s_addc_u32 s11, s87, 0
	s_mov_b32 s24, 1
	s_mov_b64 s[14:15], 0
	v_mov_b32_e32 v0, 0
	s_branch .LBB0_1062

; __device__ __forceinline__ unsigned xb_ld(unsigned* p)              { return __hip_atomic_load(p, __ATOMIC_RELAXED, __HIP_MEMORY_SCOPE_AGENT); }
; __device__ __forceinline__ unsigned xb_add(unsigned* p, unsigned v) { return __hip_atomic_fetch_add(p, v, __ATOMIC_RELAXED, __HIP_MEMORY_SCOPE_AGENT); }
; #define XB_SPIN(cond, bar) do { unsigned _sp = 0; while (cond) { __builtin_amdgcn_s_sleep(1); \
;     if ((++_sp & 255u) == 0u) { if (xb_ld(&(bar)[XB_TMO])) break; if (_sp > XB_SPIN_CAP) { atomicAdd(&(bar)[XB_TMO], 1u); break; } } } } while (0)
; __device__ __forceinline__ void xcd_barrier(const XcdBarrier& b) {
;     ...
;             __builtin_amdgcn_fence(__ATOMIC_RELEASE, "agent");
;             asm volatile("s_waitcnt vmcnt(0)" ::: "memory");
;             const unsigned og = xb_add(&bar[XB_TOP], 1u);
;             const unsigned tg = og / nx;
;             if (og + 1u == (tg + 1u) * nx) xb_add(&bar[XB_TOPGEN], 1u);
;             else XB_SPIN(xb_ld(&bar[XB_TOPGEN]) == tg, bar);
;             __builtin_amdgcn_fence(__ATOMIC_ACQUIRE, "agent");
;             xb_add(&bar[XB_XGEN(b.x)], 1u);
.LBB0_1089:
	s_or_b64 exec, exec, s[6:7]
	s_mov_b64 s[6:7], exec
	v_mbcnt_lo_u32_b32 v0, s6, 0
	v_mbcnt_hi_u32_b32 v0, s7, v0
	v_cmp_eq_u32_e32 vcc, 0, v0
	s_waitcnt vmcnt(0)
	s_and_saveexec_b64 s[8:9], vcc
	s_cbranch_execz .LBB0_1091
	s_bcnt1_i32_b64 s6, s[6:7]
	v_mov_b32_e32 v0, 0x2000
	v_mov_b32_e32 v1, s6
	global_atomic_add v0, v1, s[4:5] offset:1024
